# v70 + GEMM accumulators zeroed per unit with 64 v_mov_b64 instead of 128 v_mov_b32 (exposed unit-prologue VALU)
# speedup vs baseline: 1.0023x; 1.0023x over previous
; template <class Epi>
; DI void gemm_phase(LAS unsigned char* lds, int wid, int K, int lda, int ldb, bool bperm, const Sched3& S, const Epi& E) {
;     ...
; #pragma unroll
;         for (int a = 0; a < 2; ++a)
; #pragma unroll
;             for (int b = 0; b < 2; ++b)
; #pragma unroll
;                 for (int m = 0; m < 4; ++m)
; #pragma unroll
;                     for (int n = 0; n < 2; ++n) acc[a][b][m][n] = (f32x4){0.f, 0.f, 0.f, 0.f};
;         cur = nxt; cA = nA; cB = nB; hA = nhA; ++ui;
.LBB0_326:
	s_xor_b64 s[44:45], s[52:53], -1
	s_and_b64 s[50:51], s[52:53], exec
	s_cselect_b32 s5, s41, s47
	s_cselect_b32 s37, s40, s46
	s_cselect_b32 s39, s43, s49
	s_cselect_b32 s52, s42, s48
	s_add_u32 s46, s46, 0x80080
	s_addc_u32 s47, s47, 0
	s_add_u32 s53, s48, 0x100
	v_mov_b64_e32 v[0:1], 0
	s_addc_u32 s54, s49, 0
	s_mov_b32 s55, -2
	v_mov_b64_e32 v[2:3], 0
	v_mov_b64_e32 v[4:5], 0
	v_mov_b64_e32 v[6:7], 0
	v_mov_b64_e32 v[8:9], 0
	v_mov_b64_e32 v[10:11], 0
	v_mov_b64_e32 v[12:13], 0
	v_mov_b64_e32 v[14:15], 0
	v_mov_b64_e32 v[16:17], 0
	v_mov_b64_e32 v[18:19], 0
	v_mov_b64_e32 v[20:21], 0
	v_mov_b64_e32 v[22:23], 0
	v_mov_b64_e32 v[24:25], 0
	v_mov_b64_e32 v[26:27], 0
	v_mov_b64_e32 v[28:29], 0
	v_mov_b64_e32 v[30:31], 0
	v_mov_b64_e32 v[32:33], 0
	v_mov_b64_e32 v[34:35], 0
	v_mov_b64_e32 v[36:37], 0
	v_mov_b64_e32 v[38:39], 0
	v_mov_b64_e32 v[40:41], 0
	v_mov_b64_e32 v[42:43], 0
	v_mov_b64_e32 v[44:45], 0
	v_mov_b64_e32 v[46:47], 0
	v_mov_b64_e32 v[48:49], 0
	v_mov_b64_e32 v[50:51], 0
	v_mov_b64_e32 v[52:53], 0
	v_mov_b64_e32 v[54:55], 0
	v_mov_b64_e32 v[56:57], 0
	v_mov_b64_e32 v[58:59], 0
	v_mov_b64_e32 v[60:61], 0
	v_mov_b64_e32 v[62:63], 0
	v_mov_b64_e32 v[64:65], 0
	v_mov_b64_e32 v[66:67], 0
	v_mov_b64_e32 v[68:69], 0
	v_mov_b64_e32 v[70:71], 0
	v_mov_b64_e32 v[72:73], 0
	v_mov_b64_e32 v[74:75], 0
	v_mov_b64_e32 v[76:77], 0
	v_mov_b64_e32 v[78:79], 0
	v_mov_b64_e32 v[80:81], 0
	v_mov_b64_e32 v[82:83], 0
	v_mov_b64_e32 v[84:85], 0
	v_mov_b64_e32 v[86:87], 0
	v_mov_b64_e32 v[88:89], 0
	v_mov_b64_e32 v[90:91], 0
	v_mov_b64_e32 v[92:93], 0
	v_mov_b64_e32 v[94:95], 0
	v_mov_b64_e32 v[96:97], 0
	v_mov_b64_e32 v[98:99], 0
	v_mov_b64_e32 v[100:101], 0
	v_mov_b64_e32 v[102:103], 0
	v_mov_b64_e32 v[104:105], 0
	v_mov_b64_e32 v[106:107], 0
	v_mov_b64_e32 v[108:109], 0
	v_mov_b64_e32 v[110:111], 0
	v_mov_b64_e32 v[112:113], 0
	v_mov_b64_e32 v[114:115], 0
	v_mov_b64_e32 v[116:117], 0
	v_mov_b64_e32 v[118:119], 0
	v_mov_b64_e32 v[120:121], 0
	v_mov_b64_e32 v[122:123], 0
	v_mov_b64_e32 v[124:125], 0
	v_mov_b64_e32 v[126:127], 0

; template <class Epi>
; DI void gemm_phase(LAS unsigned char* lds, int wid, int K, int lda, int ldb, bool bperm, const Sched3& S, const Epi& E) {
;     ...
; #pragma unroll
;         for (int a = 0; a < 2; ++a)
; #pragma unroll
;             for (int b = 0; b < 2; ++b)
; #pragma unroll
;                 for (int m = 0; m < 4; ++m)
; #pragma unroll
;                     for (int n = 0; n < 2; ++n) acc[a][b][m][n] = (f32x4){0.f, 0.f, 0.f, 0.f};
;         cur = nxt; cA = nA; cB = nB; hA = nhA; ++ui;
.LBB0_620:
	s_add_u32 s38, s38, 0x80080
	s_addc_u32 s39, s39, 0
	s_add_u32 s21, s40, 0x100
	v_mov_b64_e32 v[0:1], 0
	s_addc_u32 s23, s41, 0
	s_mov_b32 s29, -2
	s_waitcnt lgkmcnt(0)
	v_mov_b64_e32 v[2:3], 0
	v_mov_b64_e32 v[4:5], 0
	v_mov_b64_e32 v[6:7], 0
	v_mov_b64_e32 v[8:9], 0
	v_mov_b64_e32 v[10:11], 0
	v_mov_b64_e32 v[12:13], 0
	v_mov_b64_e32 v[14:15], 0
	v_mov_b64_e32 v[16:17], 0
	v_mov_b64_e32 v[18:19], 0
	v_mov_b64_e32 v[20:21], 0
	v_mov_b64_e32 v[22:23], 0
	v_mov_b64_e32 v[24:25], 0
	v_mov_b64_e32 v[26:27], 0
	v_mov_b64_e32 v[28:29], 0
	v_mov_b64_e32 v[30:31], 0
	v_mov_b64_e32 v[32:33], 0
	v_mov_b64_e32 v[34:35], 0
	v_mov_b64_e32 v[36:37], 0
	v_mov_b64_e32 v[38:39], 0
	v_mov_b64_e32 v[40:41], 0
	v_mov_b64_e32 v[42:43], 0
	v_mov_b64_e32 v[44:45], 0
	v_mov_b64_e32 v[46:47], 0
	v_mov_b64_e32 v[48:49], 0
	v_mov_b64_e32 v[50:51], 0
	v_mov_b64_e32 v[52:53], 0
	v_mov_b64_e32 v[54:55], 0
	v_mov_b64_e32 v[56:57], 0
	v_mov_b64_e32 v[58:59], 0
	v_mov_b64_e32 v[60:61], 0
	v_mov_b64_e32 v[62:63], 0
	v_mov_b64_e32 v[64:65], 0
	v_mov_b64_e32 v[66:67], 0
	v_mov_b64_e32 v[68:69], 0
	v_mov_b64_e32 v[70:71], 0
	v_mov_b64_e32 v[72:73], 0
	v_mov_b64_e32 v[74:75], 0
	v_mov_b64_e32 v[76:77], 0
	v_mov_b64_e32 v[78:79], 0
	v_mov_b64_e32 v[80:81], 0
	v_mov_b64_e32 v[82:83], 0
	v_mov_b64_e32 v[84:85], 0
	v_mov_b64_e32 v[86:87], 0
	v_mov_b64_e32 v[88:89], 0
	v_mov_b64_e32 v[90:91], 0
	v_mov_b64_e32 v[92:93], 0
	v_mov_b64_e32 v[94:95], 0
	v_mov_b64_e32 v[96:97], 0
	v_mov_b64_e32 v[98:99], 0
	v_mov_b64_e32 v[100:101], 0
	v_mov_b64_e32 v[102:103], 0
	v_mov_b64_e32 v[104:105], 0
	v_mov_b64_e32 v[106:107], 0
	v_mov_b64_e32 v[108:109], 0
	v_mov_b64_e32 v[110:111], 0
	v_mov_b64_e32 v[112:113], 0
	v_mov_b64_e32 v[114:115], 0
	v_mov_b64_e32 v[116:117], 0
	v_mov_b64_e32 v[118:119], 0
	v_mov_b64_e32 v[120:121], 0
	v_mov_b64_e32 v[122:123], 0
	v_mov_b64_e32 v[124:125], 0
	v_mov_b64_e32 v[126:127], 0

; template <class Epi>
; DI void gemm_phase(LAS unsigned char* lds, int wid, int K, int lda, int ldb, bool bperm, const Sched3& S, const Epi& E) {
;     ...
; #pragma unroll
;         for (int a = 0; a < 2; ++a)
; #pragma unroll
;             for (int b = 0; b < 2; ++b)
; #pragma unroll
;                 for (int m = 0; m < 4; ++m)
; #pragma unroll
;                     for (int n = 0; n < 2; ++n) acc[a][b][m][n] = (f32x4){0.f, 0.f, 0.f, 0.f};
;         cur = nxt; cA = nA; cB = nB; hA = nhA; ++ui;
.LBB0_704:
	v_lshl_add_u32 v218, s22, 8, v155
	v_lshlrev_b32_e32 v218, 2, v218
	global_load_dword v220, v218, s[10:11]
	global_load_dword v221, v218, s[10:11] offset:64
	global_load_dword v222, v218, s[10:11] offset:128
	global_load_dword v223, v218, s[10:11] offset:192
	global_load_dword v224, v218, s[10:11] offset:512
	global_load_dword v225, v218, s[10:11] offset:576
	global_load_dword v226, v218, s[10:11] offset:640
	global_load_dword v227, v218, s[10:11] offset:704
	s_add_u32 s28, s28, 0x80080
	s_addc_u32 s29, s29, 0
	s_add_u32 s15, s30, 0x100
	v_mov_b64_e32 v[0:1], 0
	s_addc_u32 s17, s31, 0
	s_mov_b32 s57, -2
	v_mov_b64_e32 v[2:3], 0
	v_mov_b64_e32 v[4:5], 0
	v_mov_b64_e32 v[6:7], 0
	v_mov_b64_e32 v[8:9], 0
	v_mov_b64_e32 v[10:11], 0
	v_mov_b64_e32 v[12:13], 0
	v_mov_b64_e32 v[14:15], 0
	v_mov_b64_e32 v[16:17], 0
	v_mov_b64_e32 v[18:19], 0
	v_mov_b64_e32 v[20:21], 0
	v_mov_b64_e32 v[22:23], 0
	v_mov_b64_e32 v[24:25], 0
	v_mov_b64_e32 v[26:27], 0
	v_mov_b64_e32 v[28:29], 0
	v_mov_b64_e32 v[30:31], 0
	v_mov_b64_e32 v[32:33], 0
	v_mov_b64_e32 v[34:35], 0
	v_mov_b64_e32 v[36:37], 0
	v_mov_b64_e32 v[38:39], 0
	v_mov_b64_e32 v[40:41], 0
	v_mov_b64_e32 v[42:43], 0
	v_mov_b64_e32 v[44:45], 0
	v_mov_b64_e32 v[46:47], 0
	v_mov_b64_e32 v[48:49], 0
	v_mov_b64_e32 v[50:51], 0
	v_mov_b64_e32 v[52:53], 0
	v_mov_b64_e32 v[54:55], 0
	v_mov_b64_e32 v[56:57], 0
	v_mov_b64_e32 v[58:59], 0
	v_mov_b64_e32 v[60:61], 0
	v_mov_b64_e32 v[62:63], 0
	v_mov_b64_e32 v[64:65], 0
	v_mov_b64_e32 v[66:67], 0
	v_mov_b64_e32 v[68:69], 0
	v_mov_b64_e32 v[70:71], 0
	v_mov_b64_e32 v[72:73], 0
	v_mov_b64_e32 v[74:75], 0
	v_mov_b64_e32 v[76:77], 0
	v_mov_b64_e32 v[78:79], 0
	v_mov_b64_e32 v[80:81], 0
	v_mov_b64_e32 v[82:83], 0
	v_mov_b64_e32 v[84:85], 0
	v_mov_b64_e32 v[86:87], 0
	v_mov_b64_e32 v[88:89], 0
	v_mov_b64_e32 v[90:91], 0
	v_mov_b64_e32 v[92:93], 0
	v_mov_b64_e32 v[94:95], 0
	v_mov_b64_e32 v[96:97], 0
	v_mov_b64_e32 v[98:99], 0
	v_mov_b64_e32 v[100:101], 0
	v_mov_b64_e32 v[102:103], 0
	v_mov_b64_e32 v[104:105], 0
	v_mov_b64_e32 v[106:107], 0
	v_mov_b64_e32 v[108:109], 0
	v_mov_b64_e32 v[110:111], 0
	v_mov_b64_e32 v[112:113], 0
	v_mov_b64_e32 v[114:115], 0
	v_mov_b64_e32 v[116:117], 0
	v_mov_b64_e32 v[118:119], 0
	v_mov_b64_e32 v[120:121], 0
	v_mov_b64_e32 v[122:123], 0
	v_mov_b64_e32 v[124:125], 0
	v_mov_b64_e32 v[126:127], 0

; template <class Epi>
; DI void gemm_phase(LAS unsigned char* lds, int wid, int K, int lda, int ldb, bool bperm, const Sched3& S, const Epi& E) {
;     ...
; #pragma unroll
;         for (int a = 0; a < 2; ++a)
; #pragma unroll
;             for (int b = 0; b < 2; ++b)
; #pragma unroll
;                 for (int m = 0; m < 4; ++m)
; #pragma unroll
;                     for (int n = 0; n < 2; ++n) acc[a][b][m][n] = (f32x4){0.f, 0.f, 0.f, 0.f};
;         cur = nxt; cA = nA; cB = nB; hA = nhA; ++ui;
.LBB0_784:
	s_add_u32 s60, s28, 0x100
	v_mov_b64_e32 v[0:1], 0
	s_addc_u32 s61, s29, 0
	s_mov_b32 s62, -2
	s_waitcnt lgkmcnt(0)
	v_mov_b64_e32 v[2:3], 0
	v_mov_b64_e32 v[4:5], 0
	v_mov_b64_e32 v[6:7], 0
	v_mov_b64_e32 v[8:9], 0
	v_mov_b64_e32 v[10:11], 0
	v_mov_b64_e32 v[12:13], 0
	v_mov_b64_e32 v[14:15], 0
	v_mov_b64_e32 v[16:17], 0
	v_mov_b64_e32 v[18:19], 0
	v_mov_b64_e32 v[20:21], 0
	v_mov_b64_e32 v[22:23], 0
	v_mov_b64_e32 v[24:25], 0
	v_mov_b64_e32 v[26:27], 0
	v_mov_b64_e32 v[28:29], 0
	v_mov_b64_e32 v[30:31], 0
	v_mov_b64_e32 v[32:33], 0
	v_mov_b64_e32 v[34:35], 0
	v_mov_b64_e32 v[36:37], 0
	v_mov_b64_e32 v[38:39], 0
	v_mov_b64_e32 v[40:41], 0
	v_mov_b64_e32 v[42:43], 0
	v_mov_b64_e32 v[44:45], 0
	v_mov_b64_e32 v[46:47], 0
	v_mov_b64_e32 v[48:49], 0
	v_mov_b64_e32 v[50:51], 0
	v_mov_b64_e32 v[52:53], 0
	v_mov_b64_e32 v[54:55], 0
	v_mov_b64_e32 v[56:57], 0
	v_mov_b64_e32 v[58:59], 0
	v_mov_b64_e32 v[60:61], 0
	v_mov_b64_e32 v[62:63], 0
	v_mov_b64_e32 v[64:65], 0
	v_mov_b64_e32 v[66:67], 0
	v_mov_b64_e32 v[68:69], 0
	v_mov_b64_e32 v[70:71], 0
	v_mov_b64_e32 v[72:73], 0
	v_mov_b64_e32 v[74:75], 0
	v_mov_b64_e32 v[76:77], 0
	v_mov_b64_e32 v[78:79], 0
	v_mov_b64_e32 v[80:81], 0
	v_mov_b64_e32 v[82:83], 0
	v_mov_b64_e32 v[84:85], 0
	v_mov_b64_e32 v[86:87], 0
	v_mov_b64_e32 v[88:89], 0
	v_mov_b64_e32 v[90:91], 0
	v_mov_b64_e32 v[92:93], 0
	v_mov_b64_e32 v[94:95], 0
	v_mov_b64_e32 v[96:97], 0
	v_mov_b64_e32 v[98:99], 0
	v_mov_b64_e32 v[100:101], 0
	v_mov_b64_e32 v[102:103], 0
	v_mov_b64_e32 v[104:105], 0
	v_mov_b64_e32 v[106:107], 0
	v_mov_b64_e32 v[108:109], 0
	v_mov_b64_e32 v[110:111], 0
	v_mov_b64_e32 v[112:113], 0
	v_mov_b64_e32 v[114:115], 0
	v_mov_b64_e32 v[116:117], 0
	v_mov_b64_e32 v[118:119], 0
	v_mov_b64_e32 v[120:121], 0
	v_mov_b64_e32 v[122:123], 0
	v_mov_b64_e32 v[124:125], 0
	v_mov_b64_e32 v[126:127], 0

; template <class Epi>
; DI void gemm_phase(LAS unsigned char* lds, int wid, int K, int lda, int ldb, bool bperm, const Sched3& S, const Epi& E) {
;     ...
; #pragma unroll
;         for (int a = 0; a < 2; ++a)
; #pragma unroll
;             for (int b = 0; b < 2; ++b)
; #pragma unroll
;                 for (int m = 0; m < 4; ++m)
; #pragma unroll
;                     for (int n = 0; n < 2; ++n) acc[a][b][m][n] = (f32x4){0.f, 0.f, 0.f, 0.f};
;         cur = nxt; cA = nA; cB = nB; hA = nhA; ++ui;
.LBB0_872:
	s_add_u32 s36, s36, 0x80080
	s_addc_u32 s37, s37, 0
	s_add_u32 s19, s38, 0x100
	v_mov_b64_e32 v[0:1], 0
	s_addc_u32 s21, s39, 0
	s_mov_b32 s27, -2
	s_waitcnt lgkmcnt(0)
	v_mov_b64_e32 v[2:3], 0
	v_mov_b64_e32 v[4:5], 0
	v_mov_b64_e32 v[6:7], 0
	v_mov_b64_e32 v[8:9], 0
	v_mov_b64_e32 v[10:11], 0
	v_mov_b64_e32 v[12:13], 0
	v_mov_b64_e32 v[14:15], 0
	v_mov_b64_e32 v[16:17], 0
	v_mov_b64_e32 v[18:19], 0
	v_mov_b64_e32 v[20:21], 0
	v_mov_b64_e32 v[22:23], 0
	v_mov_b64_e32 v[24:25], 0
	v_mov_b64_e32 v[26:27], 0
	v_mov_b64_e32 v[28:29], 0
	v_mov_b64_e32 v[30:31], 0
	v_mov_b64_e32 v[32:33], 0
	v_mov_b64_e32 v[34:35], 0
	v_mov_b64_e32 v[36:37], 0
	v_mov_b64_e32 v[38:39], 0
	v_mov_b64_e32 v[40:41], 0
	v_mov_b64_e32 v[42:43], 0
	v_mov_b64_e32 v[44:45], 0
	v_mov_b64_e32 v[46:47], 0
	v_mov_b64_e32 v[48:49], 0
	v_mov_b64_e32 v[50:51], 0
	v_mov_b64_e32 v[52:53], 0
	v_mov_b64_e32 v[54:55], 0
	v_mov_b64_e32 v[56:57], 0
	v_mov_b64_e32 v[58:59], 0
	v_mov_b64_e32 v[60:61], 0
	v_mov_b64_e32 v[62:63], 0
	v_mov_b64_e32 v[64:65], 0
	v_mov_b64_e32 v[66:67], 0
	v_mov_b64_e32 v[68:69], 0
	v_mov_b64_e32 v[70:71], 0
	v_mov_b64_e32 v[72:73], 0
	v_mov_b64_e32 v[74:75], 0
	v_mov_b64_e32 v[76:77], 0
	v_mov_b64_e32 v[78:79], 0
	v_mov_b64_e32 v[80:81], 0
	v_mov_b64_e32 v[82:83], 0
	v_mov_b64_e32 v[84:85], 0
	v_mov_b64_e32 v[86:87], 0
	v_mov_b64_e32 v[88:89], 0
	v_mov_b64_e32 v[90:91], 0
	v_mov_b64_e32 v[92:93], 0
	v_mov_b64_e32 v[94:95], 0
	v_mov_b64_e32 v[96:97], 0
	v_mov_b64_e32 v[98:99], 0
	v_mov_b64_e32 v[100:101], 0
	v_mov_b64_e32 v[102:103], 0
	v_mov_b64_e32 v[104:105], 0
	v_mov_b64_e32 v[106:107], 0
	v_mov_b64_e32 v[108:109], 0
	v_mov_b64_e32 v[110:111], 0
	v_mov_b64_e32 v[112:113], 0
	v_mov_b64_e32 v[114:115], 0
	v_mov_b64_e32 v[116:117], 0
	v_mov_b64_e32 v[118:119], 0
	v_mov_b64_e32 v[120:121], 0
	v_mov_b64_e32 v[122:123], 0
	v_mov_b64_e32 v[124:125], 0
	v_mov_b64_e32 v[126:127], 0

; template <class Epi>
; DI void gemm_phase(LAS unsigned char* lds, int wid, int K, int lda, int ldb, bool bperm, const Sched3& S, const Epi& E) {
;     ...
; #pragma unroll
;         for (int a = 0; a < 2; ++a)
; #pragma unroll
;             for (int b = 0; b < 2; ++b)
; #pragma unroll
;                 for (int m = 0; m < 4; ++m)
; #pragma unroll
;                     for (int n = 0; n < 2; ++n) acc[a][b][m][n] = (f32x4){0.f, 0.f, 0.f, 0.f};
;         cur = nxt; cA = nA; cB = nB; hA = nhA; ++ui;
.LBB0_995:
	s_xor_b64 s[48:49], s[56:57], -1
	s_and_b64 s[56:57], s[56:57], exec
	s_cselect_b32 s41, s45, s53
	s_cselect_b32 s43, s44, s52
	s_cselect_b32 s51, s47, s55
	s_cselect_b32 s58, s46, s54
	s_add_u32 s52, s52, 0x20080
	s_addc_u32 s53, s53, 0
	s_add_u32 s59, s54, 0x100
	v_mov_b64_e32 v[0:1], 0
	s_addc_u32 s60, s55, 0
	s_mov_b32 s61, -2
	v_mov_b64_e32 v[2:3], 0
	v_mov_b64_e32 v[4:5], 0
	v_mov_b64_e32 v[6:7], 0
	v_mov_b64_e32 v[8:9], 0
	v_mov_b64_e32 v[10:11], 0
	v_mov_b64_e32 v[12:13], 0
	v_mov_b64_e32 v[14:15], 0
	v_mov_b64_e32 v[16:17], 0
	v_mov_b64_e32 v[18:19], 0
	v_mov_b64_e32 v[20:21], 0
	v_mov_b64_e32 v[22:23], 0
	v_mov_b64_e32 v[24:25], 0
	v_mov_b64_e32 v[26:27], 0
	v_mov_b64_e32 v[28:29], 0
	v_mov_b64_e32 v[30:31], 0
	v_mov_b64_e32 v[32:33], 0
	v_mov_b64_e32 v[34:35], 0
	v_mov_b64_e32 v[36:37], 0
	v_mov_b64_e32 v[38:39], 0
	v_mov_b64_e32 v[40:41], 0
	v_mov_b64_e32 v[42:43], 0
	v_mov_b64_e32 v[44:45], 0
	v_mov_b64_e32 v[46:47], 0
	v_mov_b64_e32 v[48:49], 0
	v_mov_b64_e32 v[50:51], 0
	v_mov_b64_e32 v[52:53], 0
	v_mov_b64_e32 v[54:55], 0
	v_mov_b64_e32 v[56:57], 0
	v_mov_b64_e32 v[58:59], 0
	v_mov_b64_e32 v[60:61], 0
	v_mov_b64_e32 v[62:63], 0
	v_mov_b64_e32 v[64:65], 0
	v_mov_b64_e32 v[66:67], 0
	v_mov_b64_e32 v[68:69], 0
	v_mov_b64_e32 v[70:71], 0
	v_mov_b64_e32 v[72:73], 0
	v_mov_b64_e32 v[74:75], 0
	v_mov_b64_e32 v[76:77], 0
	v_mov_b64_e32 v[78:79], 0
	v_mov_b64_e32 v[80:81], 0
	v_mov_b64_e32 v[82:83], 0
	v_mov_b64_e32 v[84:85], 0
	v_mov_b64_e32 v[86:87], 0
	v_mov_b64_e32 v[88:89], 0
	v_mov_b64_e32 v[90:91], 0
	v_mov_b64_e32 v[92:93], 0
	v_mov_b64_e32 v[94:95], 0
	v_mov_b64_e32 v[96:97], 0
	v_mov_b64_e32 v[98:99], 0
	v_mov_b64_e32 v[100:101], 0
	v_mov_b64_e32 v[102:103], 0
	v_mov_b64_e32 v[104:105], 0
	v_mov_b64_e32 v[106:107], 0
	v_mov_b64_e32 v[108:109], 0
	v_mov_b64_e32 v[110:111], 0
	v_mov_b64_e32 v[112:113], 0
	v_mov_b64_e32 v[114:115], 0
	v_mov_b64_e32 v[116:117], 0
	v_mov_b64_e32 v[118:119], 0
	v_mov_b64_e32 v[120:121], 0
	v_mov_b64_e32 v[122:123], 0
	v_mov_b64_e32 v[124:125], 0
	v_mov_b64_e32 v[126:127], 0
